# act stores (SwiGLU epilogue) marked non-temporal
# speedup vs baseline: 1.0134x; 1.0001x over previous
; __device__ __forceinline__ unsigned cvt_pk_bf16(float lo, float hi) { unsigned r; asm("v_cvt_pk_bf16_f32 %0, %1, %2" : "=v"(r) : "v"(lo), "v"(hi)); return r; }
;     __device__ __forceinline__ void operator()(const Acc& acc, const Unit& u, int wr, int wc, int fr, int fq) const {
;         const int row0 = u.pm * BM + wr * 64 + fr, col0 = u.pn * HALF + wc * 32 + 8 * fq;
;         float rrv[8];
; #pragma unroll
;         for (int q = 0; q < 8; ++q) rrv[q] = lr[wr * 64 + fr + (q >> 2) * HALF + (q & 3) * 16];
; #pragma unroll
;         for (int ai = 0; ai < 2; ++ai)
; #pragma unroll
;             for (int m = 0; m < 4; ++m) {
;                 const int row = row0 + ai * HALF + m * 16;
;                 const float rr = rrv[ai * 4 + m];
;                 float r[8];
; #pragma unroll
;                 for (int n = 0; n < 2; ++n)
; #pragma unroll
;                     for (int j = 0; j < 4; ++j) {
;                         const float g = acc[ai][0][m][n][j] * rr, up = acc[ai][1][m][n][j] * rr;
;                         r[n * 4 + j] = g * __builtin_amdgcn_rcpf(1.f + __builtin_amdgcn_exp2f(-g * LOG2E)) * up;
;                     }
;                 u32x4 w; w.x = cvt_pk_bf16(r[0], r[1]); w.y = cvt_pk_bf16(r[2], r[3]); w.z = cvt_pk_bf16(r[4], r[5]); w.w = cvt_pk_bf16(r[6], r[7]);
;                 *(u32x4*)(O + (size_t)row * DFF + col0) = w;
;             }
;     }
.LBB0_684:
	ds_read2_b32 v[144:145], v150 offset1:16
	ds_read2_b32 v[142:143], v150 offset0:32 offset1:48
	ds_read2_b32 v[140:141], v150 offset0:128 offset1:144
	ds_read2_b32 v[138:139], v150 offset0:160 offset1:176
	s_movk_i32 s24, 0x2c00
	s_andn2_b64 vcc, exec, s[14:15]
	s_mov_b32 s49, 0x60000
	s_mov_b32 s52, 0x24000
	s_mov_b32 s53, 0x28000
	s_mov_b32 s58, 0x34000
	s_mov_b32 s59, 0x38000
	s_mov_b32 s60, 0x3c000
	s_mov_b32 s61, 0x44000
	s_mov_b32 s62, 0x48000
	s_mov_b32 s63, 0x4c000
	v_lshl_or_b32 v146, s0, 7, v151
	v_lshl_add_u32 v153, s1, 8, v148
	v_ashrrev_i32_e32 v147, 31, v146
	v_mov_b64_e32 v[154:155], s[10:11]
	v_lshlrev_b64 v[156:157], 1, v[146:147]
	v_mov_b32_e32 v166, 1.0
	s_waitcnt lgkmcnt(0)
	v_mul_f32_e32 v164, 0xbfb8aa3b, v144
	v_mul_f32_e32 v165, v144, v144
	v_pk_mul_f32 v[120:121], v[124:125], v[120:121]
	v_pk_mul_f32 v[122:123], v[126:127], v[122:123]
	v_pk_mul_f32 v[112:113], v[116:117], v[112:113]
	v_pk_mul_f32 v[114:115], v[118:119], v[114:115]
	v_pk_mul_f32 v[124:125], v[124:125], v[164:165] op_sel_hi:[1,0]
	v_pk_mul_f32 v[126:127], v[126:127], v[164:165] op_sel_hi:[1,0]
	v_pk_mul_f32 v[116:117], v[116:117], v[164:165] op_sel_hi:[1,0]
	v_pk_mul_f32 v[118:119], v[118:119], v[164:165] op_sel_hi:[1,0]
	v_exp_f32_e32 v124, v124
	v_exp_f32_e32 v125, v125
	v_exp_f32_e32 v126, v126
	v_exp_f32_e32 v127, v127
	v_exp_f32_e32 v116, v116
	v_exp_f32_e32 v117, v117
	v_exp_f32_e32 v118, v118
	v_exp_f32_e32 v119, v119
	v_pk_mul_f32 v[120:121], v[120:121], v[164:165] op_sel:[0,1] op_sel_hi:[1,1]
	v_pk_mul_f32 v[122:123], v[122:123], v[164:165] op_sel:[0,1] op_sel_hi:[1,1]
	v_pk_mul_f32 v[112:113], v[112:113], v[164:165] op_sel:[0,1] op_sel_hi:[1,1]
	v_pk_mul_f32 v[114:115], v[114:115], v[164:165] op_sel:[0,1] op_sel_hi:[1,1]
	v_pk_add_f32 v[124:125], v[124:125], v[166:167] op_sel_hi:[1,0]
	v_pk_add_f32 v[126:127], v[126:127], v[166:167] op_sel_hi:[1,0]
	v_pk_add_f32 v[116:117], v[116:117], v[166:167] op_sel_hi:[1,0]
	v_pk_add_f32 v[118:119], v[118:119], v[166:167] op_sel_hi:[1,0]
	v_rcp_f32_e32 v124, v124
	v_rcp_f32_e32 v125, v125
	v_rcp_f32_e32 v126, v126
	v_rcp_f32_e32 v127, v127
	v_rcp_f32_e32 v116, v116
	v_rcp_f32_e32 v117, v117
	v_rcp_f32_e32 v118, v118
	v_rcp_f32_e32 v119, v119
	v_mad_i64_i32 v[160:161], s[0:1], v153, s24, v[154:155]
	v_lshl_add_u64 v[160:161], v[160:161], 0, v[156:157]
	v_pk_mul_f32 v[120:121], v[120:121], v[124:125]
	v_pk_mul_f32 v[122:123], v[122:123], v[126:127]
	v_pk_mul_f32 v[112:113], v[112:113], v[116:117]
	v_pk_mul_f32 v[114:115], v[114:115], v[118:119]
	v_cvt_pk_bf16_f32 v124, v120, v121
	v_cvt_pk_bf16_f32 v125, v122, v123
	v_cvt_pk_bf16_f32 v126, v112, v113
	v_cvt_pk_bf16_f32 v127, v114, v115
	global_store_dwordx4 v[160:161], v[124:127], off nt
	v_mul_f32_e32 v164, 0xbfb8aa3b, v145
	v_mul_f32_e32 v165, v145, v145
	v_pk_mul_f32 v[104:105], v[108:109], v[104:105]
	v_pk_mul_f32 v[106:107], v[110:111], v[106:107]
	v_pk_mul_f32 v[96:97], v[100:101], v[96:97]
	v_pk_mul_f32 v[98:99], v[102:103], v[98:99]
	v_pk_mul_f32 v[108:109], v[108:109], v[164:165] op_sel_hi:[1,0]
	v_pk_mul_f32 v[110:111], v[110:111], v[164:165] op_sel_hi:[1,0]
	v_pk_mul_f32 v[100:101], v[100:101], v[164:165] op_sel_hi:[1,0]
	v_pk_mul_f32 v[102:103], v[102:103], v[164:165] op_sel_hi:[1,0]
	v_exp_f32_e32 v108, v108
	v_exp_f32_e32 v109, v109
	v_exp_f32_e32 v110, v110
	v_exp_f32_e32 v111, v111
	v_exp_f32_e32 v100, v100
	v_exp_f32_e32 v101, v101
	v_exp_f32_e32 v102, v102
	v_exp_f32_e32 v103, v103
	v_pk_mul_f32 v[104:105], v[104:105], v[164:165] op_sel:[0,1] op_sel_hi:[1,1]
	v_pk_mul_f32 v[106:107], v[106:107], v[164:165] op_sel:[0,1] op_sel_hi:[1,1]
	v_pk_mul_f32 v[96:97], v[96:97], v[164:165] op_sel:[0,1] op_sel_hi:[1,1]
	v_pk_mul_f32 v[98:99], v[98:99], v[164:165] op_sel:[0,1] op_sel_hi:[1,1]
	v_pk_add_f32 v[108:109], v[108:109], v[166:167] op_sel_hi:[1,0]
	v_pk_add_f32 v[110:111], v[110:111], v[166:167] op_sel_hi:[1,0]
	v_pk_add_f32 v[100:101], v[100:101], v[166:167] op_sel_hi:[1,0]
	v_pk_add_f32 v[102:103], v[102:103], v[166:167] op_sel_hi:[1,0]
	v_rcp_f32_e32 v108, v108
	v_rcp_f32_e32 v109, v109
	v_rcp_f32_e32 v110, v110
	v_rcp_f32_e32 v111, v111
	v_rcp_f32_e32 v100, v100
	v_rcp_f32_e32 v101, v101
	v_rcp_f32_e32 v102, v102
	v_rcp_f32_e32 v103, v103
	v_add_u32_e32 v158, 0x10, v153
	v_mad_i64_i32 v[162:163], s[0:1], v158, s24, v[154:155]
	v_lshl_add_u64 v[162:163], v[162:163], 0, v[156:157]
	v_pk_mul_f32 v[104:105], v[104:105], v[108:109]
	v_pk_mul_f32 v[106:107], v[106:107], v[110:111]
	v_pk_mul_f32 v[96:97], v[96:97], v[100:101]
	v_pk_mul_f32 v[98:99], v[98:99], v[102:103]
	v_cvt_pk_bf16_f32 v108, v104, v105
	v_cvt_pk_bf16_f32 v109, v106, v107
	v_cvt_pk_bf16_f32 v110, v96, v97
	v_cvt_pk_bf16_f32 v111, v98, v99
	global_store_dwordx4 v[162:163], v[108:111], off nt
	v_mul_f32_e32 v164, 0xbfb8aa3b, v142
	v_mul_f32_e32 v165, v142, v142
	v_pk_mul_f32 v[88:89], v[92:93], v[88:89]
	v_pk_mul_f32 v[90:91], v[94:95], v[90:91]
	v_pk_mul_f32 v[80:81], v[84:85], v[80:81]
	v_pk_mul_f32 v[82:83], v[86:87], v[82:83]
	v_pk_mul_f32 v[92:93], v[92:93], v[164:165] op_sel_hi:[1,0]
	v_pk_mul_f32 v[94:95], v[94:95], v[164:165] op_sel_hi:[1,0]
	v_pk_mul_f32 v[84:85], v[84:85], v[164:165] op_sel_hi:[1,0]
	v_pk_mul_f32 v[86:87], v[86:87], v[164:165] op_sel_hi:[1,0]
	v_exp_f32_e32 v92, v92
	v_exp_f32_e32 v93, v93
	v_exp_f32_e32 v94, v94
	v_exp_f32_e32 v95, v95
	v_exp_f32_e32 v84, v84
	v_exp_f32_e32 v85, v85
	v_exp_f32_e32 v86, v86
	v_exp_f32_e32 v87, v87
	v_pk_mul_f32 v[88:89], v[88:89], v[164:165] op_sel:[0,1] op_sel_hi:[1,1]
	v_pk_mul_f32 v[90:91], v[90:91], v[164:165] op_sel:[0,1] op_sel_hi:[1,1]
	v_pk_mul_f32 v[80:81], v[80:81], v[164:165] op_sel:[0,1] op_sel_hi:[1,1]
; __device__ __forceinline__ unsigned cvt_pk_bf16(float lo, float hi) { unsigned r; asm("v_cvt_pk_bf16_f32 %0, %1, %2" : "=v"(r) : "v"(lo), "v"(hi)); return r; }
;     __device__ __forceinline__ void operator()(const Acc& acc, const Unit& u, int wr, int wc, int fr, int fq) const {
;     ...
;         for (int ai = 0; ai < 2; ++ai)
; #pragma unroll
;             for (int m = 0; m < 4; ++m) {
;                 const int row = row0 + ai * HALF + m * 16;
;                 const float rr = rrv[ai * 4 + m];
;                 float r[8];
; #pragma unroll
;                 for (int n = 0; n < 2; ++n)
; #pragma unroll
;                     for (int j = 0; j < 4; ++j) {
;                         const float g = acc[ai][0][m][n][j] * rr, up = acc[ai][1][m][n][j] * rr;
;                         r[n * 4 + j] = g * __builtin_amdgcn_rcpf(1.f + __builtin_amdgcn_exp2f(-g * LOG2E)) * up;
;                     }
;                 u32x4 w; w.x = cvt_pk_bf16(r[0], r[1]); w.y = cvt_pk_bf16(r[2], r[3]); w.z = cvt_pk_bf16(r[4], r[5]); w.w = cvt_pk_bf16(r[6], r[7]);
;                 *(u32x4*)(O + (size_t)row * DFF + col0) = w;
;             }
	v_pk_mul_f32 v[82:83], v[82:83], v[164:165] op_sel:[0,1] op_sel_hi:[1,1]
	v_pk_add_f32 v[92:93], v[92:93], v[166:167] op_sel_hi:[1,0]
	v_pk_add_f32 v[94:95], v[94:95], v[166:167] op_sel_hi:[1,0]
	v_pk_add_f32 v[84:85], v[84:85], v[166:167] op_sel_hi:[1,0]
	v_pk_add_f32 v[86:87], v[86:87], v[166:167] op_sel_hi:[1,0]
	v_rcp_f32_e32 v92, v92
	v_rcp_f32_e32 v93, v93
	v_rcp_f32_e32 v94, v94
	v_rcp_f32_e32 v95, v95
	v_rcp_f32_e32 v84, v84
	v_rcp_f32_e32 v85, v85
	v_rcp_f32_e32 v86, v86
	v_rcp_f32_e32 v87, v87
	v_add_u32_e32 v158, 0x20, v153
	v_mad_i64_i32 v[160:161], s[0:1], v158, s24, v[154:155]
	v_lshl_add_u64 v[160:161], v[160:161], 0, v[156:157]
	v_pk_mul_f32 v[88:89], v[88:89], v[92:93]
	v_pk_mul_f32 v[90:91], v[90:91], v[94:95]
	v_pk_mul_f32 v[80:81], v[80:81], v[84:85]
	v_pk_mul_f32 v[82:83], v[82:83], v[86:87]
	v_cvt_pk_bf16_f32 v92, v88, v89
	v_cvt_pk_bf16_f32 v93, v90, v91
	v_cvt_pk_bf16_f32 v94, v80, v81
	v_cvt_pk_bf16_f32 v95, v82, v83
	global_store_dwordx4 v[160:161], v[92:95], off nt
	v_mul_f32_e32 v164, 0xbfb8aa3b, v143
	v_mul_f32_e32 v165, v143, v143
	v_pk_mul_f32 v[72:73], v[76:77], v[72:73]
	v_pk_mul_f32 v[74:75], v[78:79], v[74:75]
	v_pk_mul_f32 v[64:65], v[68:69], v[64:65]
	v_pk_mul_f32 v[66:67], v[70:71], v[66:67]
	v_pk_mul_f32 v[76:77], v[76:77], v[164:165] op_sel_hi:[1,0]
	v_pk_mul_f32 v[78:79], v[78:79], v[164:165] op_sel_hi:[1,0]
	v_pk_mul_f32 v[68:69], v[68:69], v[164:165] op_sel_hi:[1,0]
	v_pk_mul_f32 v[70:71], v[70:71], v[164:165] op_sel_hi:[1,0]
	v_exp_f32_e32 v76, v76
	v_exp_f32_e32 v77, v77
	v_exp_f32_e32 v78, v78
	v_exp_f32_e32 v79, v79
	v_exp_f32_e32 v68, v68
	v_exp_f32_e32 v69, v69
	v_exp_f32_e32 v70, v70
	v_exp_f32_e32 v71, v71
	v_pk_mul_f32 v[72:73], v[72:73], v[164:165] op_sel:[0,1] op_sel_hi:[1,1]
	v_pk_mul_f32 v[74:75], v[74:75], v[164:165] op_sel:[0,1] op_sel_hi:[1,1]
	v_pk_mul_f32 v[64:65], v[64:65], v[164:165] op_sel:[0,1] op_sel_hi:[1,1]
	v_pk_mul_f32 v[66:67], v[66:67], v[164:165] op_sel:[0,1] op_sel_hi:[1,1]
	v_pk_add_f32 v[76:77], v[76:77], v[166:167] op_sel_hi:[1,0]
	v_pk_add_f32 v[78:79], v[78:79], v[166:167] op_sel_hi:[1,0]
	v_pk_add_f32 v[68:69], v[68:69], v[166:167] op_sel_hi:[1,0]
	v_pk_add_f32 v[70:71], v[70:71], v[166:167] op_sel_hi:[1,0]
	v_rcp_f32_e32 v76, v76
	v_rcp_f32_e32 v77, v77
	v_rcp_f32_e32 v78, v78
	v_rcp_f32_e32 v79, v79
	v_rcp_f32_e32 v68, v68
	v_rcp_f32_e32 v69, v69
	v_rcp_f32_e32 v70, v70
	v_rcp_f32_e32 v71, v71
	v_add_u32_e32 v158, 0x30, v153
	v_mad_i64_i32 v[162:163], s[0:1], v158, s24, v[154:155]
	v_lshl_add_u64 v[162:163], v[162:163], 0, v[156:157]
	v_pk_mul_f32 v[72:73], v[72:73], v[76:77]
	v_pk_mul_f32 v[74:75], v[74:75], v[78:79]
	v_pk_mul_f32 v[64:65], v[64:65], v[68:69]
	v_pk_mul_f32 v[66:67], v[66:67], v[70:71]
	v_cvt_pk_bf16_f32 v76, v72, v73
	v_cvt_pk_bf16_f32 v77, v74, v75
	v_cvt_pk_bf16_f32 v78, v64, v65
	v_cvt_pk_bf16_f32 v79, v66, v67
	global_store_dwordx4 v[162:163], v[76:79], off nt
	v_mul_f32_e32 v164, 0xbfb8aa3b, v140
	v_mul_f32_e32 v165, v140, v140
	v_pk_mul_f32 v[56:57], v[60:61], v[56:57]
	v_pk_mul_f32 v[58:59], v[62:63], v[58:59]
	v_pk_mul_f32 v[48:49], v[52:53], v[48:49]
	v_pk_mul_f32 v[50:51], v[54:55], v[50:51]
	v_pk_mul_f32 v[60:61], v[60:61], v[164:165] op_sel_hi:[1,0]
	v_pk_mul_f32 v[62:63], v[62:63], v[164:165] op_sel_hi:[1,0]
	v_pk_mul_f32 v[52:53], v[52:53], v[164:165] op_sel_hi:[1,0]
	v_pk_mul_f32 v[54:55], v[54:55], v[164:165] op_sel_hi:[1,0]
	v_exp_f32_e32 v60, v60
	v_exp_f32_e32 v61, v61
	v_exp_f32_e32 v62, v62
	v_exp_f32_e32 v63, v63
	v_exp_f32_e32 v52, v52
	v_exp_f32_e32 v53, v53
	v_exp_f32_e32 v54, v54
	v_exp_f32_e32 v55, v55
	v_pk_mul_f32 v[56:57], v[56:57], v[164:165] op_sel:[0,1] op_sel_hi:[1,1]
	v_pk_mul_f32 v[58:59], v[58:59], v[164:165] op_sel:[0,1] op_sel_hi:[1,1]
	v_pk_mul_f32 v[48:49], v[48:49], v[164:165] op_sel:[0,1] op_sel_hi:[1,1]
	v_pk_mul_f32 v[50:51], v[50:51], v[164:165] op_sel:[0,1] op_sel_hi:[1,1]
	v_pk_add_f32 v[60:61], v[60:61], v[166:167] op_sel_hi:[1,0]
	v_pk_add_f32 v[62:63], v[62:63], v[166:167] op_sel_hi:[1,0]
	v_pk_add_f32 v[52:53], v[52:53], v[166:167] op_sel_hi:[1,0]
	v_pk_add_f32 v[54:55], v[54:55], v[166:167] op_sel_hi:[1,0]
	v_rcp_f32_e32 v60, v60
	v_rcp_f32_e32 v61, v61
	v_rcp_f32_e32 v62, v62
	v_rcp_f32_e32 v63, v63
	v_rcp_f32_e32 v52, v52
	v_rcp_f32_e32 v53, v53
	v_rcp_f32_e32 v54, v54
	v_rcp_f32_e32 v55, v55
	v_add_u32_e32 v158, 0x80, v153
	v_mad_i64_i32 v[160:161], s[0:1], v158, s24, v[154:155]
	v_lshl_add_u64 v[160:161], v[160:161], 0, v[156:157]
	v_pk_mul_f32 v[56:57], v[56:57], v[60:61]
	v_pk_mul_f32 v[58:59], v[58:59], v[62:63]
	v_pk_mul_f32 v[48:49], v[48:49], v[52:53]
	v_pk_mul_f32 v[50:51], v[50:51], v[54:55]
	v_cvt_pk_bf16_f32 v60, v56, v57
	v_cvt_pk_bf16_f32 v61, v58, v59
	v_cvt_pk_bf16_f32 v62, v48, v49
	v_cvt_pk_bf16_f32 v63, v50, v51
	global_store_dwordx4 v[160:161], v[60:63], off nt
	v_mul_f32_e32 v164, 0xbfb8aa3b, v141
	v_mul_f32_e32 v165, v141, v141
	v_pk_mul_f32 v[40:41], v[44:45], v[40:41]
	v_pk_mul_f32 v[42:43], v[46:47], v[42:43]
	v_pk_mul_f32 v[32:33], v[36:37], v[32:33]
	v_pk_mul_f32 v[34:35], v[38:39], v[34:35]
	v_pk_mul_f32 v[44:45], v[44:45], v[164:165] op_sel_hi:[1,0]
	v_pk_mul_f32 v[46:47], v[46:47], v[164:165] op_sel_hi:[1,0]
	v_pk_mul_f32 v[36:37], v[36:37], v[164:165] op_sel_hi:[1,0]
	v_pk_mul_f32 v[38:39], v[38:39], v[164:165] op_sel_hi:[1,0]
; __device__ __forceinline__ unsigned cvt_pk_bf16(float lo, float hi) { unsigned r; asm("v_cvt_pk_bf16_f32 %0, %1, %2" : "=v"(r) : "v"(lo), "v"(hi)); return r; }
;     __device__ __forceinline__ void operator()(const Acc& acc, const Unit& u, int wr, int wc, int fr, int fq) const {
;     ...
;         for (int ai = 0; ai < 2; ++ai)
; #pragma unroll
;             for (int m = 0; m < 4; ++m) {
;                 const int row = row0 + ai * HALF + m * 16;
;                 const float rr = rrv[ai * 4 + m];
;                 float r[8];
; #pragma unroll
;                 for (int n = 0; n < 2; ++n)
; #pragma unroll
;                     for (int j = 0; j < 4; ++j) {
;                         const float g = acc[ai][0][m][n][j] * rr, up = acc[ai][1][m][n][j] * rr;
;                         r[n * 4 + j] = g * __builtin_amdgcn_rcpf(1.f + __builtin_amdgcn_exp2f(-g * LOG2E)) * up;
;                     }
;                 u32x4 w; w.x = cvt_pk_bf16(r[0], r[1]); w.y = cvt_pk_bf16(r[2], r[3]); w.z = cvt_pk_bf16(r[4], r[5]); w.w = cvt_pk_bf16(r[6], r[7]);
;                 *(u32x4*)(O + (size_t)row * DFF + col0) = w;
;             }
	v_exp_f32_e32 v44, v44
	v_exp_f32_e32 v45, v45
	v_exp_f32_e32 v46, v46
	v_exp_f32_e32 v47, v47
	v_exp_f32_e32 v36, v36
	v_exp_f32_e32 v37, v37
	v_exp_f32_e32 v38, v38
	v_exp_f32_e32 v39, v39
	v_pk_mul_f32 v[40:41], v[40:41], v[164:165] op_sel:[0,1] op_sel_hi:[1,1]
	v_pk_mul_f32 v[42:43], v[42:43], v[164:165] op_sel:[0,1] op_sel_hi:[1,1]
	v_pk_mul_f32 v[32:33], v[32:33], v[164:165] op_sel:[0,1] op_sel_hi:[1,1]
	v_pk_mul_f32 v[34:35], v[34:35], v[164:165] op_sel:[0,1] op_sel_hi:[1,1]
	v_pk_add_f32 v[44:45], v[44:45], v[166:167] op_sel_hi:[1,0]
	v_pk_add_f32 v[46:47], v[46:47], v[166:167] op_sel_hi:[1,0]
	v_pk_add_f32 v[36:37], v[36:37], v[166:167] op_sel_hi:[1,0]
	v_pk_add_f32 v[38:39], v[38:39], v[166:167] op_sel_hi:[1,0]
	v_rcp_f32_e32 v44, v44
	v_rcp_f32_e32 v45, v45
	v_rcp_f32_e32 v46, v46
	v_rcp_f32_e32 v47, v47
	v_rcp_f32_e32 v36, v36
	v_rcp_f32_e32 v37, v37
	v_rcp_f32_e32 v38, v38
	v_rcp_f32_e32 v39, v39
	v_add_u32_e32 v158, 0x90, v153
	v_mad_i64_i32 v[162:163], s[0:1], v158, s24, v[154:155]
	v_lshl_add_u64 v[162:163], v[162:163], 0, v[156:157]
	v_pk_mul_f32 v[40:41], v[40:41], v[44:45]
	v_pk_mul_f32 v[42:43], v[42:43], v[46:47]
	v_pk_mul_f32 v[32:33], v[32:33], v[36:37]
	v_pk_mul_f32 v[34:35], v[34:35], v[38:39]
	v_cvt_pk_bf16_f32 v44, v40, v41
	v_cvt_pk_bf16_f32 v45, v42, v43
	v_cvt_pk_bf16_f32 v46, v32, v33
	v_cvt_pk_bf16_f32 v47, v34, v35
	global_store_dwordx4 v[162:163], v[44:47], off nt
	v_mul_f32_e32 v164, 0xbfb8aa3b, v138
	v_mul_f32_e32 v165, v138, v138
	v_pk_mul_f32 v[24:25], v[28:29], v[24:25]
	v_pk_mul_f32 v[26:27], v[30:31], v[26:27]
	v_pk_mul_f32 v[16:17], v[20:21], v[16:17]
	v_pk_mul_f32 v[18:19], v[22:23], v[18:19]
	v_pk_mul_f32 v[28:29], v[28:29], v[164:165] op_sel_hi:[1,0]
	v_pk_mul_f32 v[30:31], v[30:31], v[164:165] op_sel_hi:[1,0]
	v_pk_mul_f32 v[20:21], v[20:21], v[164:165] op_sel_hi:[1,0]
	v_pk_mul_f32 v[22:23], v[22:23], v[164:165] op_sel_hi:[1,0]
	v_exp_f32_e32 v28, v28
	v_exp_f32_e32 v29, v29
	v_exp_f32_e32 v30, v30
	v_exp_f32_e32 v31, v31
	v_exp_f32_e32 v20, v20
	v_exp_f32_e32 v21, v21
	v_exp_f32_e32 v22, v22
	v_exp_f32_e32 v23, v23
	v_pk_mul_f32 v[24:25], v[24:25], v[164:165] op_sel:[0,1] op_sel_hi:[1,1]
	v_pk_mul_f32 v[26:27], v[26:27], v[164:165] op_sel:[0,1] op_sel_hi:[1,1]
	v_pk_mul_f32 v[16:17], v[16:17], v[164:165] op_sel:[0,1] op_sel_hi:[1,1]
	v_pk_mul_f32 v[18:19], v[18:19], v[164:165] op_sel:[0,1] op_sel_hi:[1,1]
	v_pk_add_f32 v[28:29], v[28:29], v[166:167] op_sel_hi:[1,0]
	v_pk_add_f32 v[30:31], v[30:31], v[166:167] op_sel_hi:[1,0]
	v_pk_add_f32 v[20:21], v[20:21], v[166:167] op_sel_hi:[1,0]
	v_pk_add_f32 v[22:23], v[22:23], v[166:167] op_sel_hi:[1,0]
	v_rcp_f32_e32 v28, v28
	v_rcp_f32_e32 v29, v29
	v_rcp_f32_e32 v30, v30
	v_rcp_f32_e32 v31, v31
	v_rcp_f32_e32 v20, v20
	v_rcp_f32_e32 v21, v21
	v_rcp_f32_e32 v22, v22
	v_rcp_f32_e32 v23, v23
	v_add_u32_e32 v158, 0xa0, v153
	v_mad_i64_i32 v[160:161], s[0:1], v158, s24, v[154:155]
	v_lshl_add_u64 v[160:161], v[160:161], 0, v[156:157]
	v_pk_mul_f32 v[24:25], v[24:25], v[28:29]
	v_pk_mul_f32 v[26:27], v[26:27], v[30:31]
	v_pk_mul_f32 v[16:17], v[16:17], v[20:21]
	v_pk_mul_f32 v[18:19], v[18:19], v[22:23]
	v_cvt_pk_bf16_f32 v28, v24, v25
	v_cvt_pk_bf16_f32 v29, v26, v27
	v_cvt_pk_bf16_f32 v30, v16, v17
	v_cvt_pk_bf16_f32 v31, v18, v19
	global_store_dwordx4 v[160:161], v[28:31], off nt
	v_mul_f32_e32 v164, 0xbfb8aa3b, v139
	v_mul_f32_e32 v165, v139, v139
	v_pk_mul_f32 v[8:9], v[12:13], v[8:9]
	v_pk_mul_f32 v[10:11], v[14:15], v[10:11]
	v_pk_mul_f32 v[0:1], v[4:5], v[0:1]
	v_pk_mul_f32 v[2:3], v[6:7], v[2:3]
	v_pk_mul_f32 v[12:13], v[12:13], v[164:165] op_sel_hi:[1,0]
	v_pk_mul_f32 v[14:15], v[14:15], v[164:165] op_sel_hi:[1,0]
	v_pk_mul_f32 v[4:5], v[4:5], v[164:165] op_sel_hi:[1,0]
	v_pk_mul_f32 v[6:7], v[6:7], v[164:165] op_sel_hi:[1,0]
	v_exp_f32_e32 v12, v12
	v_exp_f32_e32 v13, v13
	v_exp_f32_e32 v14, v14
	v_exp_f32_e32 v15, v15
	v_exp_f32_e32 v4, v4
	v_exp_f32_e32 v5, v5
	v_exp_f32_e32 v6, v6
	v_exp_f32_e32 v7, v7
	v_pk_mul_f32 v[8:9], v[8:9], v[164:165] op_sel:[0,1] op_sel_hi:[1,1]
	v_pk_mul_f32 v[10:11], v[10:11], v[164:165] op_sel:[0,1] op_sel_hi:[1,1]
	v_pk_mul_f32 v[0:1], v[0:1], v[164:165] op_sel:[0,1] op_sel_hi:[1,1]
	v_pk_mul_f32 v[2:3], v[2:3], v[164:165] op_sel:[0,1] op_sel_hi:[1,1]
	v_pk_add_f32 v[12:13], v[12:13], v[166:167] op_sel_hi:[1,0]
	v_pk_add_f32 v[14:15], v[14:15], v[166:167] op_sel_hi:[1,0]
	v_pk_add_f32 v[4:5], v[4:5], v[166:167] op_sel_hi:[1,0]
	v_pk_add_f32 v[6:7], v[6:7], v[166:167] op_sel_hi:[1,0]
	v_rcp_f32_e32 v12, v12
	v_rcp_f32_e32 v13, v13
	v_rcp_f32_e32 v14, v14
	v_rcp_f32_e32 v15, v15
	v_rcp_f32_e32 v4, v4
	v_rcp_f32_e32 v5, v5
	v_rcp_f32_e32 v6, v6
	v_rcp_f32_e32 v7, v7
	v_add_u32_e32 v158, 0xb0, v153
	v_mad_i64_i32 v[162:163], s[0:1], v158, s24, v[154:155]
	v_lshl_add_u64 v[162:163], v[162:163], 0, v[156:157]
	v_pk_mul_f32 v[8:9], v[8:9], v[12:13]
	v_pk_mul_f32 v[10:11], v[10:11], v[14:15]
	v_pk_mul_f32 v[0:1], v[0:1], v[4:5]
	v_pk_mul_f32 v[2:3], v[2:3], v[6:7]
	v_cvt_pk_bf16_f32 v12, v8, v9
	v_cvt_pk_bf16_f32 v13, v10, v11
	v_cvt_pk_bf16_f32 v14, v0, v1
	v_cvt_pk_bf16_f32 v15, v2, v3
	s_mov_b64 s[0:1], -1
	global_store_dwordx4 v[162:163], v[12:15], off nt
	s_cbranch_vccnz .LBB0_679
	s_andn2_b64 vcc, exec, s[8:9]
	s_cbranch_vccnz .LBB0_678
	s_barrier
	s_branch .LBB0_678
